# k28: attention loop-edge edit continued: next tile's V-fragment read base (shift + add) formed in front of each per-tile barrier
# baseline (speedup 1.0000x reference)
.LBB0_1330:
	v_lshlrev_b32_e32 v49, 1, v48
	v_lshlrev_b32_e32 v48, 4, v48
	v_and_b32_e32 v235, 32, v49
	v_and_b32_e32 v48, 0xc0, v48
	v_lshl_or_b32 v233, v242, 8, v48
	v_add_u32_e32 v48, 0, v235
	v_add3_u32 v239, v48, v232, v233
	v_max3_f32 v48, v32, v33, v16
	v_max3_f32 v49, v34, v35, v17
	s_and_b32 s5, s5, 0x3fffffc0
	v_max3_f32 v48, v48, v18, v19
	v_max3_f32 v49, v49, v38, v39
	s_lshl_b32 s5, s5, 2
	v_max3_f32 v48, v48, v36, v37
	v_max3_f32 v49, v49, v22, v23
	s_add_i32 s6, s68, 0x100
	v_max3_f32 v48, v48, v20, v21
	v_max3_f32 v49, v49, v42, v43
	s_add_i32 s75, s5, 0
	v_max3_f32 v48, v48, v40, v41
	v_max3_f32 v49, v49, v26, v27
	s_add_i32 s75, s75, 0x12000
	v_max3_f32 v48, v48, v24, v25
	v_max3_f32 v49, v49, v46, v47
	s_lshr_b32 s67, s6, 6
	v_max3_f32 v48, v48, v44, v45
	v_max3_f32 v49, v49, v30, v31
	s_cmp_lg_u32 0, -1
	v_max3_f32 v48, v48, v28, v29
	s_mov_b32 s10, 1
	v_max_f32_e32 v48, v48, v49
	s_mov_b32 s38, 0
	v_mov_b32_e32 v49, v48
	s_nop 1
	v_permlane32_swap_b32_e32 v48, v49
	v_max_f32_e32 v48, v48, v49
	v_lshlrev_b32_e32 v240, 4, v242
	v_add_f32_e32 v237, v213, v48
	v_sub_f32_e32 v16, v16, v48
	v_sub_f32_e32 v17, v17, v48
	v_sub_f32_e32 v32, v32, v48
	v_sub_f32_e32 v33, v33, v48
	v_sub_f32_e32 v34, v34, v48
	s_nop 0
	v_xor_b32_e32 v64, 0x80000000, v237
	v_mov_b32_e32 v65, v64
	v_mov_b32_e32 v66, v64
	v_mov_b32_e32 v67, v64
	v_mov_b32_e32 v68, v64
	v_mov_b32_e32 v69, v64
	v_mov_b32_e32 v70, v64
	v_mov_b32_e32 v71, v64
	v_mov_b32_e32 v72, v64
	v_mov_b32_e32 v73, v64
	v_mov_b32_e32 v74, v64
	v_mov_b32_e32 v75, v64
	v_mov_b32_e32 v76, v64
	v_mov_b32_e32 v77, v64
	v_mov_b32_e32 v78, v64
	v_mov_b32_e32 v79, v64
	s_waitcnt vmcnt(0) lgkmcnt(0)
	s_barrier
	v_exp_f32_e32 v80, v16
	v_exp_f32_e32 v81, v17
	v_lshl_add_u64 v[16:17], v[214:215], 0, s[18:19]
	s_mov_b32 m0, s76
	s_nop 0
	global_load_lds_dwordx4 v[16:17], off
	s_cselect_b32 s5, 0, 0
	s_add_i32 s4, s5, s4
	v_lshl_add_u64 v[16:17], v[216:217], 0, s[14:15]
	s_add_i32 s5, s4, 0xa000
	s_mov_b32 m0, s5
	s_nop 0
	global_load_lds_dwordx4 v[16:17], off
	v_lshl_add_u64 v[16:17], v[216:217], 0, s[20:21]
	s_add_i32 s4, s4, 0xc000
	s_mov_b32 m0, s4
	s_nop 0
	global_load_lds_dwordx4 v[16:17], off
	ds_read_b128 v[204:207], v238 offset:8192
	ds_read_b128 v[200:203], v238 offset:8704
	ds_read_b128 v[196:199], v238 offset:10240
	ds_read_b128 v[192:195], v238 offset:10752
	ds_read_b128 v[188:191], v238 offset:12288
	ds_read_b128 v[184:187], v238 offset:12800
	ds_read_b128 v[180:183], v238 offset:14336
	ds_read_b128 v[176:179], v238 offset:14848
	v_sub_f32_e32 v18, v18, v48
	v_sub_f32_e32 v35, v35, v48
	v_sub_f32_e32 v19, v19, v48
	v_sub_f32_e32 v36, v36, v48
	v_sub_f32_e32 v20, v20, v48
	v_sub_f32_e32 v37, v37, v48
	v_sub_f32_e32 v21, v21, v48
	v_sub_f32_e32 v38, v38, v48
	v_sub_f32_e32 v22, v22, v48
	v_sub_f32_e32 v39, v39, v48
	v_sub_f32_e32 v23, v23, v48
	v_sub_f32_e32 v40, v40, v48
	v_sub_f32_e32 v24, v24, v48
	v_sub_f32_e32 v41, v41, v48
	v_sub_f32_e32 v25, v25, v48
	v_sub_f32_e32 v42, v42, v48
	v_sub_f32_e32 v26, v26, v48
	v_sub_f32_e32 v43, v43, v48
	v_sub_f32_e32 v27, v27, v48
	v_sub_f32_e32 v44, v44, v48
	v_sub_f32_e32 v28, v28, v48
	v_sub_f32_e32 v45, v45, v48
	v_sub_f32_e32 v29, v29, v48
	v_sub_f32_e32 v46, v46, v48
	v_sub_f32_e32 v30, v30, v48
	v_sub_f32_e32 v47, v47, v48
	v_sub_f32_e32 v31, v31, v48
	v_exp_f32_e32 v96, v32
	v_exp_f32_e32 v97, v33
	v_exp_f32_e32 v98, v34
	v_exp_f32_e32 v99, v35
	v_exp_f32_e32 v100, v36
	v_exp_f32_e32 v101, v37
	v_exp_f32_e32 v102, v38
	v_exp_f32_e32 v103, v39
	v_exp_f32_e32 v104, v40
	v_exp_f32_e32 v105, v41
	v_exp_f32_e32 v106, v42
	v_exp_f32_e32 v107, v43
	v_exp_f32_e32 v108, v44
	v_exp_f32_e32 v109, v45
	v_exp_f32_e32 v110, v46
	v_exp_f32_e32 v111, v47
	v_exp_f32_e32 v82, v18
	v_exp_f32_e32 v83, v19
	v_exp_f32_e32 v84, v20
	v_exp_f32_e32 v85, v21
	v_exp_f32_e32 v86, v22
	v_exp_f32_e32 v87, v23
	v_exp_f32_e32 v88, v24
	v_exp_f32_e32 v89, v25
	v_exp_f32_e32 v90, v26
	v_exp_f32_e32 v91, v27
	v_exp_f32_e32 v92, v28
	v_exp_f32_e32 v93, v29
	v_exp_f32_e32 v94, v30
	v_exp_f32_e32 v95, v31
	s_waitcnt vmcnt(3) lgkmcnt(0)
	s_barrier
	v_cndmask_b32_e64 v16, 0, 1, s[8:9]
	s_add_i32 s70, s67, -5
	v_cmp_ne_u32_e64 s[6:7], 1, v16
	s_andn2_b64 vcc, exec, s[8:9]
	v_cmp_gt_u32_e64 s[8:9], 32, v231
	v_lshl_add_u32 v234, v230, 2, s75
	s_cbranch_vccnz .LBB0_1346
	v_mov_b64_e32 v[62:63], v[14:15]
	v_mov_b64_e32 v[46:47], v[14:15]
	v_mov_b64_e32 v[30:31], v[14:15]
	v_lshl_add_u64 v[220:221], v[218:219], 0, s[18:19]
	v_lshl_add_u64 v[222:223], v[216:217], 0, s[18:19]
	v_lshl_add_u64 v[224:225], v[214:215], 0, s[22:23]
	s_nop 0
	v_readfirstlane_b32 s98, v224
	v_readfirstlane_b32 s99, v225
	v_readfirstlane_b32 s100, v222
	v_readfirstlane_b32 s101, v223
	s_nop 1
	v_subrev_u32_e32 v248, s98, v224
	v_subrev_u32_e32 v250, s100, v222
	s_add_u32 s98, s98, s24
	s_addc_u32 s99, s99, s25
	s_add_u32 s100, s100, s24
	s_addc_u32 s101, s101, s25
	v_add_u32_e32 v249, 0x20000, v248
	v_add_u32_e32 v251, 0x20000, v250
	v_add_u32_e32 v252, 0x80, v250
	v_add_u32_e32 v253, 0x80, v251
	s_movk_i32 s38, 0x4000
	s_movk_i32 s11, 0x2000
	s_mov_b32 s4, 0
	v_mov_b32_e32 v243, v239
	v_mov_b32_e32 v241, 0
	v_mov_b64_e32 v[60:61], v[12:13]
	v_mov_b64_e32 v[58:59], v[10:11]
	v_mov_b64_e32 v[56:57], v[8:9]
	v_mov_b64_e32 v[54:55], v[6:7]
	v_mov_b64_e32 v[52:53], v[4:5]
	v_mov_b64_e32 v[50:51], v[2:3]
	v_mov_b64_e32 v[48:49], v[0:1]
	v_mov_b64_e32 v[44:45], v[12:13]
	v_mov_b64_e32 v[42:43], v[10:11]
	v_mov_b64_e32 v[40:41], v[8:9]
	v_mov_b64_e32 v[38:39], v[6:7]
	v_mov_b64_e32 v[36:37], v[4:5]
	v_mov_b64_e32 v[34:35], v[2:3]
	v_mov_b64_e32 v[32:33], v[0:1]
	v_mov_b64_e32 v[28:29], v[12:13]
	v_mov_b64_e32 v[26:27], v[10:11]
	v_mov_b64_e32 v[24:25], v[8:9]
	v_mov_b64_e32 v[22:23], v[6:7]
	v_mov_b64_e32 v[20:21], v[4:5]
	v_mov_b64_e32 v[18:19], v[2:3]
	v_mov_b64_e32 v[16:17], v[0:1]
.LBB0_1332:
	ds_read_b64_tr_b16 v[208:209], v243 offset:24576
	ds_read_b64_tr_b16 v[210:211], v243 offset:25088
	s_waitcnt lgkmcnt(9)
	v_mfma_f32_32x32x16_bf16 v[128:143], v[204:207], v[172:175], v[64:79]
	v_add_f32_e32 v112, v96, v97
	v_add_f32_e32 v112, v98, v112
	v_add_f32_e32 v112, v99, v112
	v_add_f32_e32 v112, v100, v112
	v_add_f32_e32 v112, v101, v112
	v_cvt_pk_bf16_f32 v164, v96, v97
	v_cvt_pk_bf16_f32 v165, v98, v99
	ds_read_b64_tr_b16 v[96:97], v243 offset:28672
	ds_read_b64_tr_b16 v[98:99], v243 offset:29184
	v_add_f32_e32 v112, v102, v112
	v_add_f32_e32 v112, v103, v112
	v_add_f32_e32 v112, v104, v112
	v_add_f32_e32 v144, v105, v112
	s_waitcnt lgkmcnt(10)
	v_mfma_f32_32x32x16_bf16 v[112:127], v[200:203], v[172:175], v[64:79]
	v_cvt_pk_bf16_f32 v166, v100, v101
	v_cvt_pk_bf16_f32 v167, v102, v103
	ds_read_b64_tr_b16 v[100:101], v243 offset:25600
	ds_read_b64_tr_b16 v[102:103], v243 offset:26112
	s_waitcnt lgkmcnt(11)
	v_mfma_f32_32x32x16_bf16 v[128:143], v[196:199], v[168:171], v[128:143]
	v_add_f32_e32 v144, v106, v144
	v_add_f32_e32 v144, v107, v144
	v_add_f32_e32 v144, v108, v144
	v_add_f32_e32 v144, v109, v144
	v_cvt_pk_bf16_f32 v156, v104, v105
	v_cvt_pk_bf16_f32 v157, v106, v107
	ds_read_b64_tr_b16 v[104:105], v243 offset:29696
	ds_read_b64_tr_b16 v[106:107], v243 offset:30208
	s_waitcnt lgkmcnt(12)
	v_mfma_f32_32x32x16_bf16 v[112:127], v[192:195], v[168:171], v[112:127]
	v_add_f32_e32 v144, v110, v144
	v_add_f32_e32 v144, v111, v144
	v_add_f32_e32 v144, v80, v144
	v_add_f32_e32 v144, v81, v144
	v_cvt_pk_bf16_f32 v158, v108, v109
	v_cvt_pk_bf16_f32 v159, v110, v111
	ds_read_b64_tr_b16 v[108:109], v243 offset:26624
	ds_read_b64_tr_b16 v[110:111], v243 offset:27136
	s_waitcnt lgkmcnt(13)
	v_mfma_f32_32x32x16_bf16 v[128:143], v[188:191], v[160:163], v[128:143]
	v_add_f32_e32 v144, v82, v144
	v_add_f32_e32 v144, v83, v144
	v_add_f32_e32 v144, v84, v144
	v_add_f32_e32 v144, v85, v144
	v_cvt_pk_bf16_f32 v148, v80, v81
	v_cvt_pk_bf16_f32 v149, v82, v83
	ds_read_b64_tr_b16 v[80:81], v243 offset:30720
	ds_read_b64_tr_b16 v[82:83], v243 offset:31232
	s_waitcnt lgkmcnt(14)
	v_mfma_f32_32x32x16_bf16 v[112:127], v[184:187], v[160:163], v[112:127]
	v_add_f32_e32 v144, v86, v144
	v_add_f32_e32 v144, v87, v144
	v_add_f32_e32 v144, v88, v144
	v_add_f32_e32 v144, v89, v144
	v_cvt_pk_bf16_f32 v150, v84, v85
	v_cvt_pk_bf16_f32 v151, v86, v87
	ds_read_b64_tr_b16 v[84:85], v243 offset:27648
	ds_read_b64_tr_b16 v[86:87], v243 offset:28160
	s_waitcnt lgkmcnt(14)
	v_mfma_f32_32x32x16_bf16 v[128:143], v[180:183], v[152:155], v[128:143]
	v_add_f32_e32 v144, v90, v144
	v_add_f32_e32 v144, v91, v144
	v_add_f32_e32 v144, v92, v144
	v_add_f32_e32 v184, v93, v144
	v_cvt_pk_bf16_f32 v144, v88, v89
	v_cvt_pk_bf16_f32 v145, v90, v91
	ds_read_b64_tr_b16 v[88:89], v243 offset:31744
	ds_read_b64_tr_b16 v[90:91], v243 offset:32256
	v_mfma_f32_32x32x16_bf16 v[112:127], v[176:179], v[152:155], v[112:127]
	v_add_f32_e32 v146, v94, v184
	v_add_f32_e32 v146, v95, v146
	v_add_f32_e32 v241, v241, v146
	v_cvt_pk_bf16_f32 v146, v92, v93
	v_cvt_pk_bf16_f32 v147, v94, v95
	s_add_i32 s4, s11, s76
	s_mov_b32 m0, s4
	s_nop 0
	global_load_lds_dwordx4 v248, s[98:99]
	s_lshl_b32 s4, s38, 1
	s_add_i32 s4, s4, s77
	s_mov_b32 m0, s4
	s_nop 0
	global_load_lds_dwordx4 v250, s[100:101]
	s_addk_i32 s4, 0x2000
	s_mov_b32 m0, s4
	s_nop 0
	global_load_lds_dwordx4 v252, s[100:101]
	v_max_f32_e32 v92, v128, v129
	v_max3_f32 v93, v130, v131, v113
	v_max3_f32 v92, v92, v112, v114
	v_max3_f32 v92, v92, v115, v132
	v_max3_f32 v93, v93, v134, v135
	v_max3_f32 v92, v92, v133, v116
	v_max3_f32 v93, v93, v118, v119
	v_max3_f32 v92, v92, v117, v136
	v_max3_f32 v93, v93, v138, v139
	v_max3_f32 v92, v92, v137, v120
	v_max3_f32 v93, v93, v122, v123
	v_max3_f32 v92, v92, v121, v140
	v_max3_f32 v93, v93, v142, v143
	v_max3_f32 v92, v92, v141, v124
	v_max3_f32 v93, v93, v126, v127
	v_max3_f32 v92, v92, v125, v93
	v_mov_b32_e32 v93, v92
	s_nop 1
	v_permlane32_swap_b32_e32 v92, v93
	v_max_f32_e32 v92, v92, v93
	v_cmp_lt_f32_e32 vcc, s41, v92
	s_cmp_lg_u64 vcc, 0
	s_cselect_b64 s[36:37], -1, 0
	s_cbranch_vccnz .LBB0_1340
.LBB0_1333:
	s_waitcnt lgkmcnt(14)
	v_mfma_f32_32x32x16_bf16 v[48:63], v[164:167], v[208:211], v[48:63]
	v_exp_f32_e32 v128, v128
	v_exp_f32_e32 v129, v129
	ds_read_b64_tr_b16 v[92:93], v243 offset:32768
	ds_read_b64_tr_b16 v[94:95], v243 offset:33280
	s_waitcnt lgkmcnt(14)
	v_mfma_f32_32x32x16_bf16 v[32:47], v[164:167], v[96:99], v[32:47]
	v_exp_f32_e32 v130, v130
	v_exp_f32_e32 v131, v131
	ds_read_b64_tr_b16 v[96:97], v243 offset:36864
	ds_read_b64_tr_b16 v[98:99], v243 offset:37376
	s_waitcnt lgkmcnt(14)
	v_mfma_f32_32x32x16_bf16 v[48:63], v[156:159], v[100:103], v[48:63]
	v_exp_f32_e32 v132, v132
	v_exp_f32_e32 v133, v133
	ds_read_b64_tr_b16 v[100:101], v243 offset:33792
	ds_read_b64_tr_b16 v[102:103], v243 offset:34304
	s_waitcnt lgkmcnt(14)
	v_mfma_f32_32x32x16_bf16 v[32:47], v[156:159], v[104:107], v[32:47]
	v_exp_f32_e32 v134, v134
	v_exp_f32_e32 v135, v135
	ds_read_b64_tr_b16 v[104:105], v243 offset:37888
	ds_read_b64_tr_b16 v[106:107], v243 offset:38400
	s_waitcnt lgkmcnt(14)
	v_mfma_f32_32x32x16_bf16 v[48:63], v[148:151], v[108:111], v[48:63]
	v_exp_f32_e32 v136, v136
	v_exp_f32_e32 v137, v137
	ds_read_b64_tr_b16 v[108:109], v243 offset:34816
	ds_read_b64_tr_b16 v[110:111], v243 offset:35328
	s_waitcnt lgkmcnt(14)
	v_mfma_f32_32x32x16_bf16 v[32:47], v[148:151], v[80:83], v[32:47]
	v_exp_f32_e32 v138, v138
	v_exp_f32_e32 v139, v139
	ds_read_b64_tr_b16 v[196:197], v243 offset:38912
	ds_read_b64_tr_b16 v[198:199], v243 offset:39424
	s_waitcnt lgkmcnt(14)
	v_mfma_f32_32x32x16_bf16 v[48:63], v[144:147], v[84:87], v[48:63]
	v_exp_f32_e32 v140, v140
	v_exp_f32_e32 v141, v141
	ds_read_b64_tr_b16 v[84:85], v243 offset:35840
	ds_read_b64_tr_b16 v[86:87], v243 offset:36352
	s_waitcnt lgkmcnt(14)
	v_mfma_f32_32x32x16_bf16 v[32:47], v[144:147], v[88:91], v[32:47]
	v_exp_f32_e32 v142, v142
	v_exp_f32_e32 v143, v143
	ds_read_b64_tr_b16 v[88:89], v243 offset:39936
	ds_read_b64_tr_b16 v[90:91], v243 offset:40448
	s_waitcnt lgkmcnt(14)
	v_mfma_f32_32x32x16_bf16 v[16:31], v[164:167], v[92:95], v[16:31]
	v_exp_f32_e32 v112, v112
	v_exp_f32_e32 v113, v113
	s_waitcnt lgkmcnt(12)
	v_mfma_f32_32x32x16_bf16 v[0:15], v[164:167], v[96:99], v[0:15]
	v_exp_f32_e32 v114, v114
	v_exp_f32_e32 v115, v115
	v_add_u32_e32 v92, s38, v238
	ds_read_b128 v[80:83], v92
	ds_read_b128 v[204:207], v92 offset:512
	s_waitcnt lgkmcnt(12)
	v_mfma_f32_32x32x16_bf16 v[16:31], v[156:159], v[100:103], v[16:31]
	v_exp_f32_e32 v116, v116
	v_exp_f32_e32 v117, v117
	ds_read_b128 v[200:203], v92 offset:2048
	ds_read_b128 v[192:195], v92 offset:2560
	s_waitcnt lgkmcnt(12)
	v_mfma_f32_32x32x16_bf16 v[0:15], v[156:159], v[104:107], v[0:15]
	v_exp_f32_e32 v118, v118
	v_exp_f32_e32 v119, v119
	ds_read_b128 v[188:191], v92 offset:4096
	ds_read_b128 v[184:187], v92 offset:4608
	s_waitcnt lgkmcnt(12)
	v_mfma_f32_32x32x16_bf16 v[16:31], v[148:151], v[108:111], v[16:31]
	v_exp_f32_e32 v120, v120
	v_exp_f32_e32 v121, v121
	ds_read_b128 v[180:183], v92 offset:6144
	ds_read_b128 v[176:179], v92 offset:6656
	s_waitcnt lgkmcnt(12)
	v_mfma_f32_32x32x16_bf16 v[0:15], v[148:151], v[196:199], v[0:15]
	v_exp_f32_e32 v122, v122
	v_exp_f32_e32 v123, v123
	s_waitcnt lgkmcnt(10)
	v_mfma_f32_32x32x16_bf16 v[16:31], v[144:147], v[84:87], v[16:31]
	v_exp_f32_e32 v124, v124
	v_exp_f32_e32 v125, v125
	s_waitcnt lgkmcnt(8)
	v_mfma_f32_32x32x16_bf16 v[0:15], v[144:147], v[88:91], v[0:15]
	v_exp_f32_e32 v126, v126
	v_exp_f32_e32 v127, v127
	s_add_i32 s4, s38, 0x2000
	s_cmpk_lg_i32 s38, 0x4000
	s_cselect_b32 s78, s4, 0
	s_lshl_b32 s4, s11, 1
	v_add_u32_e32 v209, s4, v239
	s_waitcnt vmcnt(3) lgkmcnt(0)
	s_barrier
	s_andn2_b64 vcc, exec, s[36:37]
	v_add_u32_e32 v208, s75, v240
	s_cbranch_vccnz .LBB0_1335
	s_waitcnt lgkmcnt(0)
	ds_read_b128 v[84:87], v208 offset:96
	ds_read_b128 v[88:91], v208 offset:64
	ds_read_b128 v[92:95], v208 offset:32
	ds_read_b128 v[96:99], v208
	s_waitcnt lgkmcnt(3)
	v_pk_mul_f32 v[60:61], v[60:61], v[84:85]
	s_waitcnt lgkmcnt(2)
	v_pk_mul_f32 v[56:57], v[56:57], v[88:89]
	s_waitcnt lgkmcnt(1)
	v_pk_mul_f32 v[52:53], v[52:53], v[92:93]
	v_pk_mul_f32 v[62:63], v[62:63], v[86:87]
	v_pk_mul_f32 v[58:59], v[58:59], v[90:91]
	v_pk_mul_f32 v[54:55], v[54:55], v[94:95]
	s_waitcnt lgkmcnt(0)
	v_pk_mul_f32 v[50:51], v[50:51], v[98:99]
	v_pk_mul_f32 v[48:49], v[48:49], v[96:97]
	v_pk_mul_f32 v[44:45], v[44:45], v[84:85]
	v_pk_mul_f32 v[40:41], v[40:41], v[88:89]
	v_pk_mul_f32 v[36:37], v[36:37], v[92:93]
	v_pk_mul_f32 v[46:47], v[46:47], v[86:87]
	v_pk_mul_f32 v[42:43], v[42:43], v[90:91]
	v_pk_mul_f32 v[38:39], v[38:39], v[94:95]
	v_pk_mul_f32 v[34:35], v[34:35], v[98:99]
	v_pk_mul_f32 v[32:33], v[32:33], v[96:97]
	v_pk_mul_f32 v[28:29], v[28:29], v[84:85]
	v_pk_mul_f32 v[24:25], v[24:25], v[88:89]
	v_pk_mul_f32 v[20:21], v[20:21], v[92:93]
	v_pk_mul_f32 v[30:31], v[30:31], v[86:87]
	v_pk_mul_f32 v[26:27], v[26:27], v[90:91]
	v_pk_mul_f32 v[22:23], v[22:23], v[94:95]
	v_pk_mul_f32 v[18:19], v[18:19], v[98:99]
	v_pk_mul_f32 v[16:17], v[16:17], v[96:97]
	v_pk_mul_f32 v[12:13], v[12:13], v[84:85]
	v_pk_mul_f32 v[8:9], v[8:9], v[88:89]
	v_pk_mul_f32 v[4:5], v[4:5], v[92:93]
	v_pk_mul_f32 v[14:15], v[14:15], v[86:87]
	v_pk_mul_f32 v[10:11], v[10:11], v[90:91]
	v_pk_mul_f32 v[6:7], v[6:7], v[94:95]
	v_pk_mul_f32 v[2:3], v[2:3], v[98:99]
	v_pk_mul_f32 v[0:1], v[0:1], v[96:97]
.LBB0_1335:
	ds_read_b64_tr_b16 v[196:197], v209 offset:24576
	ds_read_b64_tr_b16 v[198:199], v209 offset:25088
	s_waitcnt lgkmcnt(9)
	v_mfma_f32_32x32x16_bf16 v[96:111], v[80:83], v[172:175], v[64:79]
	v_add_f32_e32 v84, v128, v129
	v_add_f32_e32 v84, v130, v84
	v_add_f32_e32 v84, v131, v84
	v_add_f32_e32 v84, v132, v84
	v_add_f32_e32 v84, v133, v84
	v_cvt_pk_bf16_f32 v164, v128, v129
	v_cvt_pk_bf16_f32 v165, v130, v131
	ds_read_b64_tr_b16 v[128:129], v209 offset:28672
	ds_read_b64_tr_b16 v[130:131], v209 offset:29184
	v_add_f32_e32 v80, v134, v84
	v_add_f32_e32 v80, v135, v80
	v_add_f32_e32 v80, v136, v80
	v_add_f32_e32 v144, v137, v80
	s_waitcnt lgkmcnt(10)
	v_mfma_f32_32x32x16_bf16 v[80:95], v[204:207], v[172:175], v[64:79]
	v_cvt_pk_bf16_f32 v166, v132, v133
	v_cvt_pk_bf16_f32 v167, v134, v135
	ds_read_b64_tr_b16 v[132:133], v209 offset:25600
	ds_read_b64_tr_b16 v[134:135], v209 offset:26112
	s_waitcnt lgkmcnt(11)
	v_mfma_f32_32x32x16_bf16 v[96:111], v[200:203], v[168:171], v[96:111]
	v_add_f32_e32 v144, v138, v144
	v_add_f32_e32 v144, v139, v144
	v_add_f32_e32 v144, v140, v144
	v_add_f32_e32 v144, v141, v144
	v_cvt_pk_bf16_f32 v156, v136, v137
	v_cvt_pk_bf16_f32 v157, v138, v139
	ds_read_b64_tr_b16 v[136:137], v209 offset:29696
	ds_read_b64_tr_b16 v[138:139], v209 offset:30208
	s_waitcnt lgkmcnt(12)
	v_mfma_f32_32x32x16_bf16 v[80:95], v[192:195], v[168:171], v[80:95]
	v_add_f32_e32 v144, v142, v144
	v_add_f32_e32 v144, v143, v144
	v_add_f32_e32 v144, v112, v144
	v_add_f32_e32 v144, v113, v144
	v_cvt_pk_bf16_f32 v158, v140, v141
	v_cvt_pk_bf16_f32 v159, v142, v143
	ds_read_b64_tr_b16 v[140:141], v209 offset:26624
	ds_read_b64_tr_b16 v[142:143], v209 offset:27136
	s_waitcnt lgkmcnt(13)
	v_mfma_f32_32x32x16_bf16 v[96:111], v[188:191], v[160:163], v[96:111]
	v_add_f32_e32 v144, v114, v144
	v_add_f32_e32 v144, v115, v144
	v_add_f32_e32 v144, v116, v144
	v_add_f32_e32 v144, v117, v144
	v_cvt_pk_bf16_f32 v148, v112, v113
	v_cvt_pk_bf16_f32 v149, v114, v115
	ds_read_b64_tr_b16 v[112:113], v209 offset:30720
	ds_read_b64_tr_b16 v[114:115], v209 offset:31232
	s_waitcnt lgkmcnt(14)
	v_mfma_f32_32x32x16_bf16 v[80:95], v[184:187], v[160:163], v[80:95]
	v_add_f32_e32 v144, v118, v144
	v_add_f32_e32 v144, v119, v144
	v_add_f32_e32 v144, v120, v144
	v_add_f32_e32 v144, v121, v144
	v_cvt_pk_bf16_f32 v150, v116, v117
	v_cvt_pk_bf16_f32 v151, v118, v119
	ds_read_b64_tr_b16 v[116:117], v209 offset:27648
	ds_read_b64_tr_b16 v[118:119], v209 offset:28160
	s_waitcnt lgkmcnt(14)
	v_mfma_f32_32x32x16_bf16 v[96:111], v[180:183], v[152:155], v[96:111]
	v_add_f32_e32 v144, v122, v144
	v_add_f32_e32 v144, v123, v144
	v_add_f32_e32 v144, v124, v144
	v_add_f32_e32 v184, v125, v144
	v_cvt_pk_bf16_f32 v144, v120, v121
	v_cvt_pk_bf16_f32 v145, v122, v123
	ds_read_b64_tr_b16 v[120:121], v209 offset:31744
	ds_read_b64_tr_b16 v[122:123], v209 offset:32256
	v_mfma_f32_32x32x16_bf16 v[80:95], v[176:179], v[152:155], v[80:95]
	v_add_f32_e32 v146, v126, v184
	v_add_f32_e32 v146, v127, v146
	v_add_f32_e32 v241, v241, v146
	v_cvt_pk_bf16_f32 v146, v124, v125
	v_cvt_pk_bf16_f32 v147, v126, v127
	v_max_f32_e32 v124, v96, v97
	s_nop 3
	s_nop 1
	v_max3_f32 v125, v98, v99, v81
	v_max3_f32 v124, v124, v80, v82
	v_max3_f32 v124, v124, v83, v100
	v_max3_f32 v125, v125, v102, v103
	v_max3_f32 v124, v124, v101, v84
	v_max3_f32 v125, v125, v86, v87
	v_max3_f32 v124, v124, v85, v104
	v_max3_f32 v125, v125, v106, v107
	v_max3_f32 v124, v124, v105, v88
	v_max3_f32 v125, v125, v90, v91
	v_max3_f32 v124, v124, v89, v108
	v_max3_f32 v125, v125, v110, v111
	v_max3_f32 v124, v124, v109, v92
	v_max3_f32 v125, v125, v94, v95
	v_max3_f32 v124, v124, v93, v125
	v_mov_b32_e32 v125, v124
	s_add_i32 s4, s38, s76
	s_nop 0
	v_permlane32_swap_b32_e32 v124, v125
	s_mov_b32 m0, s4
	s_nop 0
	global_load_lds_dwordx4 v249, s[98:99]
	s_lshl_b32 s4, s78, 1
	s_add_i32 s4, s4, s77
	s_mov_b32 m0, s4
	s_nop 0
	global_load_lds_dwordx4 v251, s[100:101]
	v_max_f32_e32 v124, v124, v125
	s_addk_i32 s4, 0x2000
	s_mov_b32 m0, s4
	s_nop 0
	global_load_lds_dwordx4 v253, s[100:101]
	v_cmp_lt_f32_e32 vcc, s41, v124
	s_cmp_lg_u64 vcc, 0
	s_cselect_b64 s[36:37], -1, 0
	s_cbranch_vccnz .LBB0_1343
.LBB0_1336:
	s_waitcnt lgkmcnt(14)
	v_mfma_f32_32x32x16_bf16 v[48:63], v[164:167], v[196:199], v[48:63]
	v_exp_f32_e32 v96, v96
	v_exp_f32_e32 v97, v97
	ds_read_b64_tr_b16 v[124:125], v209 offset:32768
	ds_read_b64_tr_b16 v[126:127], v209 offset:33280
	s_waitcnt lgkmcnt(14)
	v_mfma_f32_32x32x16_bf16 v[32:47], v[164:167], v[128:131], v[32:47]
	v_exp_f32_e32 v98, v98
	v_exp_f32_e32 v99, v99
	ds_read_b64_tr_b16 v[128:129], v209 offset:36864
	ds_read_b64_tr_b16 v[130:131], v209 offset:37376
	s_waitcnt lgkmcnt(14)
	v_mfma_f32_32x32x16_bf16 v[48:63], v[156:159], v[132:135], v[48:63]
	v_exp_f32_e32 v100, v100
	v_exp_f32_e32 v101, v101
	ds_read_b64_tr_b16 v[132:133], v209 offset:33792
	ds_read_b64_tr_b16 v[134:135], v209 offset:34304
	s_waitcnt lgkmcnt(14)
	v_mfma_f32_32x32x16_bf16 v[32:47], v[156:159], v[136:139], v[32:47]
	v_exp_f32_e32 v102, v102
	v_exp_f32_e32 v103, v103
	ds_read_b64_tr_b16 v[136:137], v209 offset:37888
	ds_read_b64_tr_b16 v[138:139], v209 offset:38400
	s_waitcnt lgkmcnt(14)
	v_mfma_f32_32x32x16_bf16 v[48:63], v[148:151], v[140:143], v[48:63]
	v_exp_f32_e32 v104, v104
	v_exp_f32_e32 v105, v105
	ds_read_b64_tr_b16 v[140:141], v209 offset:34816
	ds_read_b64_tr_b16 v[142:143], v209 offset:35328
	s_waitcnt lgkmcnt(14)
	v_mfma_f32_32x32x16_bf16 v[32:47], v[148:151], v[112:115], v[32:47]
	v_exp_f32_e32 v106, v106
	v_exp_f32_e32 v107, v107
	ds_read_b64_tr_b16 v[112:113], v209 offset:38912
	ds_read_b64_tr_b16 v[114:115], v209 offset:39424
	s_waitcnt lgkmcnt(14)
	v_mfma_f32_32x32x16_bf16 v[48:63], v[144:147], v[116:119], v[48:63]
	v_exp_f32_e32 v108, v108
	v_exp_f32_e32 v109, v109
	ds_read_b64_tr_b16 v[116:117], v209 offset:35840
	ds_read_b64_tr_b16 v[118:119], v209 offset:36352
	s_waitcnt lgkmcnt(14)
	v_mfma_f32_32x32x16_bf16 v[32:47], v[144:147], v[120:123], v[32:47]
	v_exp_f32_e32 v110, v110
	v_exp_f32_e32 v111, v111
	ds_read_b64_tr_b16 v[120:121], v209 offset:39936
	ds_read_b64_tr_b16 v[122:123], v209 offset:40448
	s_waitcnt lgkmcnt(14)
	v_mfma_f32_32x32x16_bf16 v[16:31], v[164:167], v[124:127], v[16:31]
	v_exp_f32_e32 v80, v80
	v_exp_f32_e32 v81, v81
	s_waitcnt lgkmcnt(12)
	v_mfma_f32_32x32x16_bf16 v[0:15], v[164:167], v[128:131], v[0:15]
	v_exp_f32_e32 v82, v82
	v_exp_f32_e32 v83, v83
	v_add_u32_e32 v124, s78, v238
	ds_read_b128 v[204:207], v124
	ds_read_b128 v[200:203], v124 offset:512
	s_waitcnt lgkmcnt(12)
	v_mfma_f32_32x32x16_bf16 v[16:31], v[156:159], v[132:135], v[16:31]
	v_exp_f32_e32 v84, v84
	v_exp_f32_e32 v85, v85
	ds_read_b128 v[196:199], v124 offset:2048
	ds_read_b128 v[192:195], v124 offset:2560
	s_waitcnt lgkmcnt(12)
	v_mfma_f32_32x32x16_bf16 v[0:15], v[156:159], v[136:139], v[0:15]
	v_exp_f32_e32 v86, v86
	v_exp_f32_e32 v87, v87
	ds_read_b128 v[188:191], v124 offset:4096
	ds_read_b128 v[184:187], v124 offset:4608
	s_waitcnt lgkmcnt(12)
	v_mfma_f32_32x32x16_bf16 v[16:31], v[148:151], v[140:143], v[16:31]
	v_exp_f32_e32 v88, v88
	v_exp_f32_e32 v89, v89
	ds_read_b128 v[180:183], v124 offset:6144
	ds_read_b128 v[176:179], v124 offset:6656
	s_waitcnt lgkmcnt(12)
	v_mfma_f32_32x32x16_bf16 v[0:15], v[148:151], v[112:115], v[0:15]
	v_exp_f32_e32 v90, v90
	v_exp_f32_e32 v91, v91
	s_waitcnt lgkmcnt(10)
	v_mfma_f32_32x32x16_bf16 v[16:31], v[144:147], v[116:119], v[16:31]
	v_exp_f32_e32 v92, v92
	v_exp_f32_e32 v93, v93
	s_waitcnt lgkmcnt(8)
	v_mfma_f32_32x32x16_bf16 v[0:15], v[144:147], v[120:123], v[0:15]
	v_exp_f32_e32 v94, v94
	v_exp_f32_e32 v95, v95
	s_add_i32 s10, s10, 2
	s_add_i32 s4, s78, 0x2000
	s_cmpk_lg_i32 s78, 0x4000
	s_cselect_b32 s79, s4, 0
	s_add_u32 s98, s98, s16
	s_addc_u32 s99, s99, s17
	s_add_u32 s100, s100, s16
	s_addc_u32 s101, s101, s17
	s_lshl_b32 s4, s38, 1
	v_add_u32_e32 v243, s4, v239
	s_waitcnt vmcnt(3) lgkmcnt(0)
	s_barrier
	s_andn2_b64 vcc, exec, s[36:37]
	s_cbranch_vccnz .LBB0_1338
	s_waitcnt lgkmcnt(0)
	ds_read_b128 v[112:115], v208 offset:96
	ds_read_b128 v[116:119], v208 offset:64
	ds_read_b128 v[120:123], v208 offset:32
	ds_read_b128 v[124:127], v208
	s_waitcnt lgkmcnt(3)
	v_pk_mul_f32 v[60:61], v[60:61], v[112:113]
	s_waitcnt lgkmcnt(2)
	v_pk_mul_f32 v[56:57], v[56:57], v[116:117]
	s_waitcnt lgkmcnt(1)
	v_pk_mul_f32 v[52:53], v[52:53], v[120:121]
	v_pk_mul_f32 v[62:63], v[62:63], v[114:115]
	v_pk_mul_f32 v[58:59], v[58:59], v[118:119]
	v_pk_mul_f32 v[54:55], v[54:55], v[122:123]
	s_waitcnt lgkmcnt(0)
	v_pk_mul_f32 v[50:51], v[50:51], v[126:127]
	v_pk_mul_f32 v[48:49], v[48:49], v[124:125]
	v_pk_mul_f32 v[44:45], v[44:45], v[112:113]
	v_pk_mul_f32 v[40:41], v[40:41], v[116:117]
	v_pk_mul_f32 v[36:37], v[36:37], v[120:121]
	v_pk_mul_f32 v[46:47], v[46:47], v[114:115]
	v_pk_mul_f32 v[42:43], v[42:43], v[118:119]
	v_pk_mul_f32 v[38:39], v[38:39], v[122:123]
	v_pk_mul_f32 v[34:35], v[34:35], v[126:127]
	v_pk_mul_f32 v[32:33], v[32:33], v[124:125]
	v_pk_mul_f32 v[28:29], v[28:29], v[112:113]
	v_pk_mul_f32 v[24:25], v[24:25], v[116:117]
	v_pk_mul_f32 v[20:21], v[20:21], v[120:121]
	v_pk_mul_f32 v[30:31], v[30:31], v[114:115]
	v_pk_mul_f32 v[26:27], v[26:27], v[118:119]
	v_pk_mul_f32 v[22:23], v[22:23], v[122:123]
	v_pk_mul_f32 v[18:19], v[18:19], v[126:127]
	v_pk_mul_f32 v[16:17], v[16:17], v[124:125]
	v_pk_mul_f32 v[12:13], v[12:13], v[112:113]
	v_pk_mul_f32 v[8:9], v[8:9], v[116:117]
	v_pk_mul_f32 v[4:5], v[4:5], v[120:121]
	v_pk_mul_f32 v[14:15], v[14:15], v[114:115]
	v_pk_mul_f32 v[10:11], v[10:11], v[118:119]
	v_pk_mul_f32 v[6:7], v[6:7], v[122:123]
	v_pk_mul_f32 v[2:3], v[2:3], v[126:127]
	v_pk_mul_f32 v[0:1], v[0:1], v[124:125]

.LBB0_1357:
	v_lshlrev_b32_e32 v48, 1, v231
	v_and_b32_e32 v234, 32, v48
	v_lshlrev_b32_e32 v48, 4, v241
	v_and_b32_e32 v48, 0xc0, v48
	v_add_u32_e32 v49, 0, v234
	v_lshl_or_b32 v235, v244, 8, v48
	v_max3_f32 v48, v32, v33, v16
	v_add3_u32 v240, v49, v232, v235
	v_max3_f32 v49, v34, v35, v17
	v_max3_f32 v48, v48, v18, v19
	s_and_b32 s5, s5, 0x3fffffc0
	v_max3_f32 v48, v48, v36, v37
	v_max3_f32 v49, v49, v38, v39
	s_lshl_b32 s5, s5, 2
	v_max3_f32 v48, v48, v20, v21
	v_max3_f32 v49, v49, v22, v23
	s_add_i32 s49, s5, 0
	v_max3_f32 v48, v48, v40, v41
	v_max3_f32 v49, v49, v42, v43
	s_add_i32 s49, s49, 0x12000
	v_max3_f32 v48, v48, v24, v25
	v_max3_f32 v49, v49, v26, v27
	s_cmp_lg_u32 0, -1
	v_max3_f32 v48, v48, v44, v45
	v_max3_f32 v49, v49, v46, v47
	s_mov_b32 s34, 1
	v_max3_f32 v48, v48, v28, v29
	v_max3_f32 v49, v49, v30, v31
	s_mov_b32 s36, 0
	v_max_f32_e32 v48, v48, v49
	v_lshlrev_b32_e32 v242, 4, v244
	v_mov_b32_e32 v49, v48
	s_nop 1
	v_permlane32_swap_b32_e32 v48, v49
	v_max_f32_e32 v48, v48, v49
	v_lshl_add_u32 v236, v230, 2, s49
	v_add_f32_e32 v238, v213, v48
	v_sub_f32_e32 v16, v16, v48
	v_sub_f32_e32 v17, v17, v48
	v_sub_f32_e32 v32, v32, v48
	v_sub_f32_e32 v33, v33, v48
	v_sub_f32_e32 v34, v34, v48
	s_nop 0
	v_xor_b32_e32 v64, 0x80000000, v238
	v_mov_b32_e32 v65, v64
	v_mov_b32_e32 v66, v64
	v_mov_b32_e32 v67, v64
	v_mov_b32_e32 v68, v64
	v_mov_b32_e32 v69, v64
	v_mov_b32_e32 v70, v64
	v_mov_b32_e32 v71, v64
	v_mov_b32_e32 v72, v64
	v_mov_b32_e32 v73, v64
	v_mov_b32_e32 v74, v64
	v_mov_b32_e32 v75, v64
	v_mov_b32_e32 v76, v64
	v_mov_b32_e32 v77, v64
	v_mov_b32_e32 v78, v64
	v_mov_b32_e32 v79, v64
	s_waitcnt vmcnt(0) lgkmcnt(0)
	s_barrier
	v_exp_f32_e32 v80, v16
	v_exp_f32_e32 v81, v17
	v_lshl_add_u64 v[16:17], v[214:215], 0, s[18:19]
	s_mov_b32 m0, s71
	s_nop 0
	global_load_lds_dwordx4 v[16:17], off
	s_cselect_b32 s5, 0, 0
	s_add_i32 s4, s5, s4
	v_lshl_add_u64 v[16:17], v[216:217], 0, s[14:15]
	s_add_i32 s5, s4, 0xa000
	s_mov_b32 m0, s5
	s_nop 0
	global_load_lds_dwordx4 v[16:17], off
	v_lshl_add_u64 v[16:17], v[216:217], 0, s[20:21]
	s_add_i32 s4, s4, 0xc000
	s_mov_b32 m0, s4
	s_nop 0
	global_load_lds_dwordx4 v[16:17], off
	ds_read_b128 v[204:207], v239 offset:8192
	ds_read_b128 v[200:203], v239 offset:8704
	ds_read_b128 v[196:199], v239 offset:10240
	ds_read_b128 v[192:195], v239 offset:10752
	ds_read_b128 v[188:191], v239 offset:12288
	ds_read_b128 v[184:187], v239 offset:12800
	ds_read_b128 v[180:183], v239 offset:14336
	ds_read_b128 v[176:179], v239 offset:14848
	v_sub_f32_e32 v18, v18, v48
	v_sub_f32_e32 v35, v35, v48
	v_sub_f32_e32 v19, v19, v48
	v_sub_f32_e32 v36, v36, v48
	v_sub_f32_e32 v20, v20, v48
	v_sub_f32_e32 v37, v37, v48
	v_sub_f32_e32 v21, v21, v48
	v_sub_f32_e32 v38, v38, v48
	v_sub_f32_e32 v22, v22, v48
	v_sub_f32_e32 v39, v39, v48
	v_sub_f32_e32 v23, v23, v48
	v_sub_f32_e32 v40, v40, v48
	v_sub_f32_e32 v24, v24, v48
	v_sub_f32_e32 v41, v41, v48
	v_sub_f32_e32 v25, v25, v48
	v_sub_f32_e32 v42, v42, v48
	v_sub_f32_e32 v26, v26, v48
	v_sub_f32_e32 v43, v43, v48
	v_sub_f32_e32 v27, v27, v48
	v_sub_f32_e32 v44, v44, v48
	v_sub_f32_e32 v28, v28, v48
	v_sub_f32_e32 v45, v45, v48
	v_sub_f32_e32 v29, v29, v48
	v_sub_f32_e32 v46, v46, v48
	v_sub_f32_e32 v30, v30, v48
	v_sub_f32_e32 v47, v47, v48
	v_sub_f32_e32 v31, v31, v48
	v_exp_f32_e32 v96, v32
	v_exp_f32_e32 v97, v33
	v_exp_f32_e32 v98, v34
	v_exp_f32_e32 v99, v35
	v_exp_f32_e32 v100, v36
	v_exp_f32_e32 v101, v37
	v_exp_f32_e32 v102, v38
	v_exp_f32_e32 v103, v39
	v_exp_f32_e32 v104, v40
	v_exp_f32_e32 v105, v41
	v_exp_f32_e32 v106, v42
	v_exp_f32_e32 v107, v43
	v_exp_f32_e32 v108, v44
	v_exp_f32_e32 v109, v45
	v_exp_f32_e32 v110, v46
	v_exp_f32_e32 v111, v47
	v_exp_f32_e32 v82, v18
	v_exp_f32_e32 v83, v19
	v_exp_f32_e32 v84, v20
	v_exp_f32_e32 v85, v21
	v_exp_f32_e32 v86, v22
	v_exp_f32_e32 v87, v23
	v_exp_f32_e32 v88, v24
	v_exp_f32_e32 v89, v25
	v_exp_f32_e32 v90, v26
	v_exp_f32_e32 v91, v27
	v_exp_f32_e32 v92, v28
	v_exp_f32_e32 v93, v29
	v_exp_f32_e32 v94, v30
	v_exp_f32_e32 v95, v31
	s_waitcnt vmcnt(3) lgkmcnt(0)
	s_barrier
	s_and_b64 vcc, exec, s[6:7]
	v_cmp_gt_u32_e64 s[6:7], 32, v231
	s_cbranch_vccnz .LBB0_1423
	v_mov_b64_e32 v[62:63], v[14:15]
	v_mov_b64_e32 v[46:47], v[14:15]
	v_mov_b64_e32 v[30:31], v[14:15]
	v_lshl_add_u64 v[220:221], v[218:219], 0, s[18:19]
	v_lshl_add_u64 v[222:223], v[216:217], 0, s[18:19]
	v_lshl_add_u64 v[224:225], v[214:215], 0, s[22:23]
	s_nop 0
	v_readfirstlane_b32 s98, v224
	v_readfirstlane_b32 s99, v225
	v_readfirstlane_b32 s100, v222
	v_readfirstlane_b32 s101, v223
	s_nop 1
	v_subrev_u32_e32 v248, s98, v224
	v_subrev_u32_e32 v250, s100, v222
	s_add_u32 s98, s98, s24
	s_addc_u32 s99, s99, s25
	s_add_u32 s100, s100, s24
	s_addc_u32 s101, s101, s25
	v_add_u32_e32 v249, 0x20000, v248
	v_add_u32_e32 v251, 0x20000, v250
	v_add_u32_e32 v252, 0x80, v250
	v_add_u32_e32 v253, 0x80, v251
	s_movk_i32 s36, 0x4000
	s_movk_i32 s35, 0x2000
	s_mov_b32 s4, 0
	v_mov_b32_e32 v245, v240
	v_mov_b32_e32 v243, 0
	v_mov_b64_e32 v[60:61], v[12:13]
	v_mov_b64_e32 v[58:59], v[10:11]
	v_mov_b64_e32 v[56:57], v[8:9]
	v_mov_b64_e32 v[54:55], v[6:7]
	v_mov_b64_e32 v[52:53], v[4:5]
	v_mov_b64_e32 v[50:51], v[2:3]
	v_mov_b64_e32 v[48:49], v[0:1]
	v_mov_b64_e32 v[44:45], v[12:13]
	v_mov_b64_e32 v[42:43], v[10:11]
	v_mov_b64_e32 v[40:41], v[8:9]
	v_mov_b64_e32 v[38:39], v[6:7]
	v_mov_b64_e32 v[36:37], v[4:5]
	v_mov_b64_e32 v[34:35], v[2:3]
	v_mov_b64_e32 v[32:33], v[0:1]
	v_mov_b64_e32 v[28:29], v[12:13]
	v_mov_b64_e32 v[26:27], v[10:11]
	v_mov_b64_e32 v[24:25], v[8:9]
	v_mov_b64_e32 v[22:23], v[6:7]
	v_mov_b64_e32 v[20:21], v[4:5]
	v_mov_b64_e32 v[18:19], v[2:3]
	v_mov_b64_e32 v[16:17], v[0:1]
.LBB0_1359:
	ds_read_b64_tr_b16 v[208:209], v245 offset:24576
	ds_read_b64_tr_b16 v[210:211], v245 offset:25088
	s_waitcnt lgkmcnt(9)
	v_mfma_f32_32x32x16_bf16 v[128:143], v[204:207], v[172:175], v[64:79]
	v_add_f32_e32 v112, v96, v97
	v_add_f32_e32 v112, v98, v112
	v_add_f32_e32 v112, v99, v112
	v_add_f32_e32 v112, v100, v112
	v_add_f32_e32 v112, v101, v112
	v_cvt_pk_bf16_f32 v160, v96, v97
	v_cvt_pk_bf16_f32 v161, v98, v99
	ds_read_b64_tr_b16 v[96:97], v245 offset:28672
	ds_read_b64_tr_b16 v[98:99], v245 offset:29184
	v_add_f32_e32 v112, v102, v112
	v_add_f32_e32 v112, v103, v112
	v_add_f32_e32 v112, v104, v112
	v_add_f32_e32 v144, v105, v112
	s_waitcnt lgkmcnt(10)
	v_mfma_f32_32x32x16_bf16 v[112:127], v[200:203], v[172:175], v[64:79]
	v_cvt_pk_bf16_f32 v162, v100, v101
	v_cvt_pk_bf16_f32 v163, v102, v103
	ds_read_b64_tr_b16 v[100:101], v245 offset:25600
	ds_read_b64_tr_b16 v[102:103], v245 offset:26112
	s_waitcnt lgkmcnt(11)
	v_mfma_f32_32x32x16_bf16 v[128:143], v[196:199], v[168:171], v[128:143]
	v_add_f32_e32 v144, v106, v144
	v_add_f32_e32 v144, v107, v144
	v_add_f32_e32 v144, v108, v144
	v_add_f32_e32 v144, v109, v144
	v_cvt_pk_bf16_f32 v156, v104, v105
	v_cvt_pk_bf16_f32 v157, v106, v107
	ds_read_b64_tr_b16 v[104:105], v245 offset:29696
	ds_read_b64_tr_b16 v[106:107], v245 offset:30208
	s_waitcnt lgkmcnt(12)
	v_mfma_f32_32x32x16_bf16 v[112:127], v[192:195], v[168:171], v[112:127]
	v_add_f32_e32 v144, v110, v144
	v_add_f32_e32 v144, v111, v144
	v_add_f32_e32 v144, v80, v144
	v_add_f32_e32 v144, v81, v144
	v_cvt_pk_bf16_f32 v158, v108, v109
	v_cvt_pk_bf16_f32 v159, v110, v111
	ds_read_b64_tr_b16 v[108:109], v245 offset:26624
	ds_read_b64_tr_b16 v[110:111], v245 offset:27136
	s_waitcnt lgkmcnt(13)
	v_mfma_f32_32x32x16_bf16 v[128:143], v[188:191], v[164:167], v[128:143]
	v_add_f32_e32 v144, v82, v144
	v_add_f32_e32 v144, v83, v144
	v_add_f32_e32 v144, v84, v144
	v_add_f32_e32 v144, v85, v144
	v_cvt_pk_bf16_f32 v148, v80, v81
	v_cvt_pk_bf16_f32 v149, v82, v83
	ds_read_b64_tr_b16 v[80:81], v245 offset:30720
	ds_read_b64_tr_b16 v[82:83], v245 offset:31232
	s_waitcnt lgkmcnt(14)
	v_mfma_f32_32x32x16_bf16 v[112:127], v[184:187], v[164:167], v[112:127]
	v_add_f32_e32 v144, v86, v144
	v_add_f32_e32 v144, v87, v144
	v_add_f32_e32 v144, v88, v144
	v_add_f32_e32 v144, v89, v144
	v_cvt_pk_bf16_f32 v150, v84, v85
	v_cvt_pk_bf16_f32 v151, v86, v87
	ds_read_b64_tr_b16 v[84:85], v245 offset:27648
	ds_read_b64_tr_b16 v[86:87], v245 offset:28160
	s_waitcnt lgkmcnt(14)
	v_mfma_f32_32x32x16_bf16 v[128:143], v[180:183], v[152:155], v[128:143]
	v_add_f32_e32 v144, v90, v144
	v_add_f32_e32 v144, v91, v144
	v_add_f32_e32 v144, v92, v144
	v_add_f32_e32 v184, v93, v144
	v_cvt_pk_bf16_f32 v144, v88, v89
	v_cvt_pk_bf16_f32 v145, v90, v91
	ds_read_b64_tr_b16 v[88:89], v245 offset:31744
	ds_read_b64_tr_b16 v[90:91], v245 offset:32256
	v_mfma_f32_32x32x16_bf16 v[112:127], v[176:179], v[152:155], v[112:127]
	v_add_f32_e32 v146, v94, v184
	v_add_f32_e32 v146, v95, v146
	v_add_f32_e32 v180, 0, v146
	v_cvt_pk_bf16_f32 v146, v92, v93
	v_cvt_pk_bf16_f32 v147, v94, v95
	s_add_i32 s4, s35, s71
	s_mov_b32 m0, s4
	s_nop 0
	global_load_lds_dwordx4 v248, s[98:99]
	s_lshl_b32 s4, s36, 1
	s_add_i32 s4, s4, s74
	s_mov_b32 m0, s4
	s_nop 0
	global_load_lds_dwordx4 v250, s[100:101]
	s_addk_i32 s4, 0x2000
	s_mov_b32 m0, s4
	s_nop 0
	global_load_lds_dwordx4 v252, s[100:101]
	v_max_f32_e32 v92, v128, v129
	v_max3_f32 v93, v130, v131, v113
	v_max3_f32 v92, v92, v112, v114
	v_max3_f32 v92, v92, v115, v132
	v_max3_f32 v93, v93, v134, v135
	v_max3_f32 v92, v92, v133, v116
	v_max3_f32 v93, v93, v118, v119
	v_max3_f32 v92, v92, v117, v136
	v_max3_f32 v93, v93, v138, v139
	v_max3_f32 v92, v92, v137, v120
	v_max3_f32 v93, v93, v122, v123
	v_max3_f32 v92, v92, v121, v140
	v_max3_f32 v93, v93, v142, v143
	v_max3_f32 v92, v92, v141, v124
	v_max3_f32 v93, v93, v126, v127
	v_max3_f32 v92, v92, v125, v93
	v_mov_b32_e32 v93, v92
	s_nop 1
	v_permlane32_swap_b32_e32 v92, v93
	v_max_f32_e32 v92, v92, v93
	v_cmp_lt_f32_e32 vcc, s41, v92
	s_cmp_lg_u64 vcc, 0
	v_add_f32_e32 v233, v243, v180
	s_cselect_b64 s[10:11], -1, 0
	s_cbranch_vccnz .LBB0_1367
.LBB0_1360:
	s_waitcnt lgkmcnt(14)
	v_mfma_f32_32x32x16_bf16 v[48:63], v[160:163], v[208:211], v[48:63]
	v_exp_f32_e32 v128, v128
	v_exp_f32_e32 v129, v129
	ds_read_b64_tr_b16 v[92:93], v245 offset:32768
	ds_read_b64_tr_b16 v[94:95], v245 offset:33280
	s_waitcnt lgkmcnt(14)
	v_mfma_f32_32x32x16_bf16 v[32:47], v[160:163], v[96:99], v[32:47]
	v_exp_f32_e32 v130, v130
	v_exp_f32_e32 v131, v131
	ds_read_b64_tr_b16 v[96:97], v245 offset:36864
	ds_read_b64_tr_b16 v[98:99], v245 offset:37376
	s_waitcnt lgkmcnt(14)
	v_mfma_f32_32x32x16_bf16 v[48:63], v[156:159], v[100:103], v[48:63]
	v_exp_f32_e32 v132, v132
	v_exp_f32_e32 v133, v133
	ds_read_b64_tr_b16 v[100:101], v245 offset:33792
	ds_read_b64_tr_b16 v[102:103], v245 offset:34304
	s_waitcnt lgkmcnt(14)
	v_mfma_f32_32x32x16_bf16 v[32:47], v[156:159], v[104:107], v[32:47]
	v_exp_f32_e32 v134, v134
	v_exp_f32_e32 v135, v135
	ds_read_b64_tr_b16 v[104:105], v245 offset:37888
	ds_read_b64_tr_b16 v[106:107], v245 offset:38400
	s_waitcnt lgkmcnt(14)
	v_mfma_f32_32x32x16_bf16 v[48:63], v[148:151], v[108:111], v[48:63]
	v_exp_f32_e32 v136, v136
	v_exp_f32_e32 v137, v137
	ds_read_b64_tr_b16 v[108:109], v245 offset:34816
	ds_read_b64_tr_b16 v[110:111], v245 offset:35328
	s_waitcnt lgkmcnt(14)
	v_mfma_f32_32x32x16_bf16 v[32:47], v[148:151], v[80:83], v[32:47]
	v_exp_f32_e32 v138, v138
	v_exp_f32_e32 v139, v139
	ds_read_b64_tr_b16 v[196:197], v245 offset:38912
	ds_read_b64_tr_b16 v[198:199], v245 offset:39424
	s_waitcnt lgkmcnt(14)
	v_mfma_f32_32x32x16_bf16 v[48:63], v[144:147], v[84:87], v[48:63]
	v_exp_f32_e32 v140, v140
	v_exp_f32_e32 v141, v141
	ds_read_b64_tr_b16 v[84:85], v245 offset:35840
	ds_read_b64_tr_b16 v[86:87], v245 offset:36352
	s_waitcnt lgkmcnt(14)
	v_mfma_f32_32x32x16_bf16 v[32:47], v[144:147], v[88:91], v[32:47]
	v_exp_f32_e32 v142, v142
	v_exp_f32_e32 v143, v143
	ds_read_b64_tr_b16 v[88:89], v245 offset:39936
	ds_read_b64_tr_b16 v[90:91], v245 offset:40448
	s_waitcnt lgkmcnt(14)
	v_mfma_f32_32x32x16_bf16 v[16:31], v[160:163], v[92:95], v[16:31]
	v_exp_f32_e32 v112, v112
	v_exp_f32_e32 v113, v113
	s_waitcnt lgkmcnt(12)
	v_mfma_f32_32x32x16_bf16 v[0:15], v[160:163], v[96:99], v[0:15]
	v_exp_f32_e32 v114, v114
	v_exp_f32_e32 v115, v115
	v_add_u32_e32 v92, s36, v239
	ds_read_b128 v[80:83], v92
	ds_read_b128 v[204:207], v92 offset:512
	s_waitcnt lgkmcnt(12)
	v_mfma_f32_32x32x16_bf16 v[16:31], v[156:159], v[100:103], v[16:31]
	v_exp_f32_e32 v116, v116
	v_exp_f32_e32 v117, v117
	ds_read_b128 v[200:203], v92 offset:2048
	ds_read_b128 v[192:195], v92 offset:2560
	s_waitcnt lgkmcnt(12)
	v_mfma_f32_32x32x16_bf16 v[0:15], v[156:159], v[104:107], v[0:15]
	v_exp_f32_e32 v118, v118
	v_exp_f32_e32 v119, v119
	ds_read_b128 v[188:191], v92 offset:4096
	ds_read_b128 v[184:187], v92 offset:4608
	s_waitcnt lgkmcnt(12)
	v_mfma_f32_32x32x16_bf16 v[16:31], v[148:151], v[108:111], v[16:31]
	v_exp_f32_e32 v120, v120
	v_exp_f32_e32 v121, v121
	ds_read_b128 v[180:183], v92 offset:6144
	ds_read_b128 v[176:179], v92 offset:6656
	s_waitcnt lgkmcnt(12)
	v_mfma_f32_32x32x16_bf16 v[0:15], v[148:151], v[196:199], v[0:15]
	v_exp_f32_e32 v122, v122
	v_exp_f32_e32 v123, v123
	s_waitcnt lgkmcnt(10)
	v_mfma_f32_32x32x16_bf16 v[16:31], v[144:147], v[84:87], v[16:31]
	v_exp_f32_e32 v124, v124
	v_exp_f32_e32 v125, v125
	s_waitcnt lgkmcnt(8)
	v_mfma_f32_32x32x16_bf16 v[0:15], v[144:147], v[88:91], v[0:15]
	v_exp_f32_e32 v126, v126
	v_exp_f32_e32 v127, v127
	s_add_i32 s4, s36, 0x2000
	s_cmpk_lg_i32 s36, 0x4000
	s_cselect_b32 s75, s4, 0
	s_lshl_b32 s4, s35, 1
	v_add_u32_e32 v209, s4, v240
	s_waitcnt vmcnt(3) lgkmcnt(0)
	s_barrier
	s_andn2_b64 vcc, exec, s[10:11]
	v_add_u32_e32 v208, s49, v242
	s_cbranch_vccnz .LBB0_1362
	s_waitcnt lgkmcnt(0)
	ds_read_b128 v[84:87], v208 offset:96
	ds_read_b128 v[88:91], v208 offset:64
	ds_read_b128 v[92:95], v208 offset:32
	ds_read_b128 v[96:99], v208
	s_waitcnt lgkmcnt(3)
	v_pk_mul_f32 v[60:61], v[60:61], v[84:85]
	s_waitcnt lgkmcnt(2)
	v_pk_mul_f32 v[56:57], v[56:57], v[88:89]
	s_waitcnt lgkmcnt(1)
	v_pk_mul_f32 v[52:53], v[52:53], v[92:93]
	v_pk_mul_f32 v[62:63], v[62:63], v[86:87]
	v_pk_mul_f32 v[58:59], v[58:59], v[90:91]
	v_pk_mul_f32 v[54:55], v[54:55], v[94:95]
	s_waitcnt lgkmcnt(0)
	v_pk_mul_f32 v[50:51], v[50:51], v[98:99]
	v_pk_mul_f32 v[48:49], v[48:49], v[96:97]
	v_pk_mul_f32 v[44:45], v[44:45], v[84:85]
	v_pk_mul_f32 v[40:41], v[40:41], v[88:89]
	v_pk_mul_f32 v[36:37], v[36:37], v[92:93]
	v_pk_mul_f32 v[46:47], v[46:47], v[86:87]
	v_pk_mul_f32 v[42:43], v[42:43], v[90:91]
	v_pk_mul_f32 v[38:39], v[38:39], v[94:95]
	v_pk_mul_f32 v[34:35], v[34:35], v[98:99]
	v_pk_mul_f32 v[32:33], v[32:33], v[96:97]
	v_pk_mul_f32 v[28:29], v[28:29], v[84:85]
	v_pk_mul_f32 v[24:25], v[24:25], v[88:89]
	v_pk_mul_f32 v[20:21], v[20:21], v[92:93]
	v_pk_mul_f32 v[30:31], v[30:31], v[86:87]
	v_pk_mul_f32 v[26:27], v[26:27], v[90:91]
	v_pk_mul_f32 v[22:23], v[22:23], v[94:95]
	v_pk_mul_f32 v[18:19], v[18:19], v[98:99]
	v_pk_mul_f32 v[16:17], v[16:17], v[96:97]
	v_pk_mul_f32 v[12:13], v[12:13], v[84:85]
	v_pk_mul_f32 v[8:9], v[8:9], v[88:89]
	v_pk_mul_f32 v[4:5], v[4:5], v[92:93]
	v_pk_mul_f32 v[14:15], v[14:15], v[86:87]
	v_pk_mul_f32 v[10:11], v[10:11], v[90:91]
	v_pk_mul_f32 v[6:7], v[6:7], v[94:95]
	v_pk_mul_f32 v[2:3], v[2:3], v[98:99]
	v_pk_mul_f32 v[0:1], v[0:1], v[96:97]
.LBB0_1362:
	ds_read_b64_tr_b16 v[196:197], v209 offset:24576
	ds_read_b64_tr_b16 v[198:199], v209 offset:25088
	s_waitcnt lgkmcnt(9)
	v_mfma_f32_32x32x16_bf16 v[96:111], v[80:83], v[172:175], v[64:79]
	v_add_f32_e32 v84, v128, v129
	v_add_f32_e32 v84, v130, v84
	v_add_f32_e32 v84, v131, v84
	v_add_f32_e32 v84, v132, v84
	v_add_f32_e32 v84, v133, v84
	v_cvt_pk_bf16_f32 v160, v128, v129
	v_cvt_pk_bf16_f32 v161, v130, v131
	ds_read_b64_tr_b16 v[128:129], v209 offset:28672
	ds_read_b64_tr_b16 v[130:131], v209 offset:29184
	v_add_f32_e32 v80, v134, v84
	v_add_f32_e32 v80, v135, v80
	v_add_f32_e32 v80, v136, v80
	v_add_f32_e32 v144, v137, v80
	s_waitcnt lgkmcnt(10)
	v_mfma_f32_32x32x16_bf16 v[80:95], v[204:207], v[172:175], v[64:79]
	v_cvt_pk_bf16_f32 v162, v132, v133
	v_cvt_pk_bf16_f32 v163, v134, v135
	ds_read_b64_tr_b16 v[132:133], v209 offset:25600
	ds_read_b64_tr_b16 v[134:135], v209 offset:26112
	s_waitcnt lgkmcnt(11)
	v_mfma_f32_32x32x16_bf16 v[96:111], v[200:203], v[168:171], v[96:111]
	v_add_f32_e32 v144, v138, v144
	v_add_f32_e32 v144, v139, v144
	v_add_f32_e32 v144, v140, v144
	v_add_f32_e32 v144, v141, v144
	v_cvt_pk_bf16_f32 v156, v136, v137
	v_cvt_pk_bf16_f32 v157, v138, v139
	ds_read_b64_tr_b16 v[136:137], v209 offset:29696
	ds_read_b64_tr_b16 v[138:139], v209 offset:30208
	s_waitcnt lgkmcnt(12)
	v_mfma_f32_32x32x16_bf16 v[80:95], v[192:195], v[168:171], v[80:95]
	v_add_f32_e32 v144, v142, v144
	v_add_f32_e32 v144, v143, v144
	v_add_f32_e32 v144, v112, v144
	v_add_f32_e32 v144, v113, v144
	v_cvt_pk_bf16_f32 v158, v140, v141
	v_cvt_pk_bf16_f32 v159, v142, v143
	ds_read_b64_tr_b16 v[140:141], v209 offset:26624
	ds_read_b64_tr_b16 v[142:143], v209 offset:27136
	s_waitcnt lgkmcnt(13)
	v_mfma_f32_32x32x16_bf16 v[96:111], v[188:191], v[164:167], v[96:111]
	v_add_f32_e32 v144, v114, v144
	v_add_f32_e32 v144, v115, v144
	v_add_f32_e32 v144, v116, v144
	v_add_f32_e32 v144, v117, v144
	v_cvt_pk_bf16_f32 v148, v112, v113
	v_cvt_pk_bf16_f32 v149, v114, v115
	ds_read_b64_tr_b16 v[112:113], v209 offset:30720
	ds_read_b64_tr_b16 v[114:115], v209 offset:31232
	s_waitcnt lgkmcnt(14)
	v_mfma_f32_32x32x16_bf16 v[80:95], v[184:187], v[164:167], v[80:95]
	v_add_f32_e32 v144, v118, v144
	v_add_f32_e32 v144, v119, v144
	v_add_f32_e32 v144, v120, v144
	v_add_f32_e32 v144, v121, v144
	v_cvt_pk_bf16_f32 v150, v116, v117
	v_cvt_pk_bf16_f32 v151, v118, v119
	ds_read_b64_tr_b16 v[116:117], v209 offset:27648
	ds_read_b64_tr_b16 v[118:119], v209 offset:28160
	s_waitcnt lgkmcnt(14)
	v_mfma_f32_32x32x16_bf16 v[96:111], v[180:183], v[152:155], v[96:111]
	v_add_f32_e32 v144, v122, v144
	v_add_f32_e32 v144, v123, v144
	v_add_f32_e32 v144, v124, v144
	v_add_f32_e32 v184, v125, v144
	v_cvt_pk_bf16_f32 v144, v120, v121
	v_cvt_pk_bf16_f32 v145, v122, v123
	ds_read_b64_tr_b16 v[120:121], v209 offset:31744
	ds_read_b64_tr_b16 v[122:123], v209 offset:32256
	v_mfma_f32_32x32x16_bf16 v[80:95], v[176:179], v[152:155], v[80:95]
	v_add_f32_e32 v146, v126, v184
	v_add_f32_e32 v146, v127, v146
	v_add_f32_e32 v180, 0, v146
	v_cvt_pk_bf16_f32 v146, v124, v125
	v_cvt_pk_bf16_f32 v147, v126, v127
	v_max_f32_e32 v124, v96, v97
	s_nop 3
	s_nop 1
	v_max3_f32 v125, v98, v99, v81
	v_max3_f32 v124, v124, v80, v82
	v_max3_f32 v124, v124, v83, v100
	v_max3_f32 v125, v125, v102, v103
	v_max3_f32 v124, v124, v101, v84
	v_max3_f32 v125, v125, v86, v87
	v_max3_f32 v124, v124, v85, v104
	v_max3_f32 v125, v125, v106, v107
	v_max3_f32 v124, v124, v105, v88
	v_max3_f32 v125, v125, v90, v91
	v_max3_f32 v124, v124, v89, v108
	v_max3_f32 v125, v125, v110, v111
	v_max3_f32 v124, v124, v109, v92
	v_max3_f32 v125, v125, v94, v95
	v_max3_f32 v124, v124, v93, v125
	v_mov_b32_e32 v125, v124
	s_add_i32 s4, s36, s71
	s_nop 0
	v_permlane32_swap_b32_e32 v124, v125
	s_mov_b32 m0, s4
	s_nop 0
	global_load_lds_dwordx4 v249, s[98:99]
	s_lshl_b32 s4, s75, 1
	s_add_i32 s4, s4, s74
	s_mov_b32 m0, s4
	s_nop 0
	global_load_lds_dwordx4 v251, s[100:101]
	v_max_f32_e32 v124, v124, v125
	s_addk_i32 s4, 0x2000
	s_mov_b32 m0, s4
	s_nop 0
	global_load_lds_dwordx4 v253, s[100:101]
	v_cmp_lt_f32_e32 vcc, s41, v124
	s_cmp_lg_u64 vcc, 0
	v_add_f32_e32 v243, v233, v180
	s_cselect_b64 s[10:11], -1, 0
	s_cbranch_vccnz .LBB0_1370
.LBB0_1363:
	s_waitcnt lgkmcnt(14)
	v_mfma_f32_32x32x16_bf16 v[48:63], v[160:163], v[196:199], v[48:63]
	v_exp_f32_e32 v96, v96
	v_exp_f32_e32 v97, v97
	ds_read_b64_tr_b16 v[124:125], v209 offset:32768
	ds_read_b64_tr_b16 v[126:127], v209 offset:33280
	s_waitcnt lgkmcnt(14)
	v_mfma_f32_32x32x16_bf16 v[32:47], v[160:163], v[128:131], v[32:47]
	v_exp_f32_e32 v98, v98
	v_exp_f32_e32 v99, v99
	ds_read_b64_tr_b16 v[128:129], v209 offset:36864
	ds_read_b64_tr_b16 v[130:131], v209 offset:37376
	s_waitcnt lgkmcnt(14)
	v_mfma_f32_32x32x16_bf16 v[48:63], v[156:159], v[132:135], v[48:63]
	v_exp_f32_e32 v100, v100
	v_exp_f32_e32 v101, v101
	ds_read_b64_tr_b16 v[132:133], v209 offset:33792
	ds_read_b64_tr_b16 v[134:135], v209 offset:34304
	s_waitcnt lgkmcnt(14)
	v_mfma_f32_32x32x16_bf16 v[32:47], v[156:159], v[136:139], v[32:47]
	v_exp_f32_e32 v102, v102
	v_exp_f32_e32 v103, v103
	ds_read_b64_tr_b16 v[136:137], v209 offset:37888
	ds_read_b64_tr_b16 v[138:139], v209 offset:38400
	s_waitcnt lgkmcnt(14)
	v_mfma_f32_32x32x16_bf16 v[48:63], v[148:151], v[140:143], v[48:63]
	v_exp_f32_e32 v104, v104
	v_exp_f32_e32 v105, v105
	ds_read_b64_tr_b16 v[140:141], v209 offset:34816
	ds_read_b64_tr_b16 v[142:143], v209 offset:35328
	s_waitcnt lgkmcnt(14)
	v_mfma_f32_32x32x16_bf16 v[32:47], v[148:151], v[112:115], v[32:47]
	v_exp_f32_e32 v106, v106
	v_exp_f32_e32 v107, v107
	ds_read_b64_tr_b16 v[112:113], v209 offset:38912
	ds_read_b64_tr_b16 v[114:115], v209 offset:39424
	s_waitcnt lgkmcnt(14)
	v_mfma_f32_32x32x16_bf16 v[48:63], v[144:147], v[116:119], v[48:63]
	v_exp_f32_e32 v108, v108
	v_exp_f32_e32 v109, v109
	ds_read_b64_tr_b16 v[116:117], v209 offset:35840
	ds_read_b64_tr_b16 v[118:119], v209 offset:36352
	s_waitcnt lgkmcnt(14)
	v_mfma_f32_32x32x16_bf16 v[32:47], v[144:147], v[120:123], v[32:47]
	v_exp_f32_e32 v110, v110
	v_exp_f32_e32 v111, v111
	ds_read_b64_tr_b16 v[120:121], v209 offset:39936
	ds_read_b64_tr_b16 v[122:123], v209 offset:40448
	s_waitcnt lgkmcnt(14)
	v_mfma_f32_32x32x16_bf16 v[16:31], v[160:163], v[124:127], v[16:31]
	v_exp_f32_e32 v80, v80
	v_exp_f32_e32 v81, v81
	s_waitcnt lgkmcnt(12)
	v_mfma_f32_32x32x16_bf16 v[0:15], v[160:163], v[128:131], v[0:15]
	v_exp_f32_e32 v82, v82
	v_exp_f32_e32 v83, v83
	v_add_u32_e32 v124, s75, v239
	ds_read_b128 v[204:207], v124
	ds_read_b128 v[200:203], v124 offset:512
	s_waitcnt lgkmcnt(12)
	v_mfma_f32_32x32x16_bf16 v[16:31], v[156:159], v[132:135], v[16:31]
	v_exp_f32_e32 v84, v84
	v_exp_f32_e32 v85, v85
	ds_read_b128 v[196:199], v124 offset:2048
	ds_read_b128 v[192:195], v124 offset:2560
	s_waitcnt lgkmcnt(12)
	v_mfma_f32_32x32x16_bf16 v[0:15], v[156:159], v[136:139], v[0:15]
	v_exp_f32_e32 v86, v86
	v_exp_f32_e32 v87, v87
	ds_read_b128 v[188:191], v124 offset:4096
	ds_read_b128 v[184:187], v124 offset:4608
	s_waitcnt lgkmcnt(12)
	v_mfma_f32_32x32x16_bf16 v[16:31], v[148:151], v[140:143], v[16:31]
	v_exp_f32_e32 v88, v88
	v_exp_f32_e32 v89, v89
	ds_read_b128 v[180:183], v124 offset:6144
	ds_read_b128 v[176:179], v124 offset:6656
	s_waitcnt lgkmcnt(12)
	v_mfma_f32_32x32x16_bf16 v[0:15], v[148:151], v[112:115], v[0:15]
	v_exp_f32_e32 v90, v90
	v_exp_f32_e32 v91, v91
	s_waitcnt lgkmcnt(10)
	v_mfma_f32_32x32x16_bf16 v[16:31], v[144:147], v[116:119], v[16:31]
	v_exp_f32_e32 v92, v92
	v_exp_f32_e32 v93, v93
	s_waitcnt lgkmcnt(8)
	v_mfma_f32_32x32x16_bf16 v[0:15], v[144:147], v[120:123], v[0:15]
	v_exp_f32_e32 v94, v94
	v_exp_f32_e32 v95, v95
	s_add_i32 s34, s34, 2
	s_add_i32 s4, s75, 0x2000
	s_cmpk_lg_i32 s75, 0x4000
	s_cselect_b32 s76, s4, 0
	s_add_u32 s98, s98, s16
	s_addc_u32 s99, s99, s17
	s_add_u32 s100, s100, s16
	s_addc_u32 s101, s101, s17
	s_lshl_b32 s4, s36, 1
	v_add_u32_e32 v245, s4, v240
	s_waitcnt vmcnt(3) lgkmcnt(0)
	s_barrier
	s_andn2_b64 vcc, exec, s[10:11]
	s_cbranch_vccnz .LBB0_1365
	s_waitcnt lgkmcnt(0)
	ds_read_b128 v[112:115], v208 offset:96
	ds_read_b128 v[116:119], v208 offset:64
	ds_read_b128 v[120:123], v208 offset:32
	ds_read_b128 v[124:127], v208
	s_waitcnt lgkmcnt(3)
	v_pk_mul_f32 v[60:61], v[60:61], v[112:113]
	s_waitcnt lgkmcnt(2)
	v_pk_mul_f32 v[56:57], v[56:57], v[116:117]
	s_waitcnt lgkmcnt(1)
	v_pk_mul_f32 v[52:53], v[52:53], v[120:121]
	v_pk_mul_f32 v[62:63], v[62:63], v[114:115]
	v_pk_mul_f32 v[58:59], v[58:59], v[118:119]
	v_pk_mul_f32 v[54:55], v[54:55], v[122:123]
	s_waitcnt lgkmcnt(0)
	v_pk_mul_f32 v[50:51], v[50:51], v[126:127]
	v_pk_mul_f32 v[48:49], v[48:49], v[124:125]
	v_pk_mul_f32 v[44:45], v[44:45], v[112:113]
	v_pk_mul_f32 v[40:41], v[40:41], v[116:117]
	v_pk_mul_f32 v[36:37], v[36:37], v[120:121]
	v_pk_mul_f32 v[46:47], v[46:47], v[114:115]
	v_pk_mul_f32 v[42:43], v[42:43], v[118:119]
	v_pk_mul_f32 v[38:39], v[38:39], v[122:123]
	v_pk_mul_f32 v[34:35], v[34:35], v[126:127]
	v_pk_mul_f32 v[32:33], v[32:33], v[124:125]
	v_pk_mul_f32 v[28:29], v[28:29], v[112:113]
	v_pk_mul_f32 v[24:25], v[24:25], v[116:117]
	v_pk_mul_f32 v[20:21], v[20:21], v[120:121]
	v_pk_mul_f32 v[30:31], v[30:31], v[114:115]
	v_pk_mul_f32 v[26:27], v[26:27], v[118:119]
	v_pk_mul_f32 v[22:23], v[22:23], v[122:123]
	v_pk_mul_f32 v[18:19], v[18:19], v[126:127]
	v_pk_mul_f32 v[16:17], v[16:17], v[124:125]
	v_pk_mul_f32 v[12:13], v[12:13], v[112:113]
	v_pk_mul_f32 v[8:9], v[8:9], v[116:117]
	v_pk_mul_f32 v[4:5], v[4:5], v[120:121]
	v_pk_mul_f32 v[14:15], v[14:15], v[114:115]
	v_pk_mul_f32 v[10:11], v[10:11], v[118:119]
	v_pk_mul_f32 v[6:7], v[6:7], v[122:123]
	v_pk_mul_f32 v[2:3], v[2:3], v[126:127]
	v_pk_mul_f32 v[0:1], v[0:1], v[124:125]
